# N1: ff1 K-loop skips the dummy next-unit prefetch DMAs in the last iteration of a WG's final unit (vmcnt counts fixed up); on top of G1
# speedup vs baseline: 1.0243x; 1.0062x over previous
.LBB0_234:
	s_add_u32 s26, s6, 0xfffc0080
	s_addc_u32 s27, s7, -1
	s_add_i32 s90, 0, 0x10000
	s_cmp_eq_u32 s89, 12
	s_cselect_b32 s61, s31, s27
	s_cselect_b32 s60, s80, s26
	v_add_u32_e32 v144, s90, v146
	s_cselect_b32 s39, s15, s88
	s_cselect_b32 s38, s86, s87
	s_cselect_b32 s100, 1, 0
	s_cmp_lg_u64 s[36:37], 0
	s_cselect_b32 s100, 0, s100
	s_add_i32 s91, 0, 0x14000
	.p2align 6
	ds_read_b128 v[140:143], v144
	ds_read_b128 v[148:151], v144 offset:1024
	ds_read_b128 v[152:155], v144 offset:2048
	ds_read_b128 v[156:159], v144 offset:3072
	v_add_u32_e32 v144, s91, v146
	ds_read_b128 v[160:163], v144
	ds_read_b128 v[164:167], v144 offset:1024
	ds_read_b128 v[168:171], v144 offset:2048
	ds_read_b128 v[172:175], v144 offset:3072
	v_lshl_add_u64 v[144:145], s[6:7], 0, v[138:139]
	s_add_i32 m0, s65, 0xc000
	ds_read_b128 v[176:179], v147
	ds_read_b128 v[180:183], v147 offset:1024
	ds_read_b128 v[188:191], v147 offset:2048
	ds_read_b128 v[192:195], v147 offset:3072
	ds_read_b128 v[196:199], v147 offset:4096
	ds_read_b128 v[200:203], v147 offset:5120
	ds_read_b128 v[204:207], v147 offset:6144
	ds_read_b128 v[208:211], v147 offset:7168
	global_load_lds_dwordx4 v[144:145], off
	v_lshl_add_u64 v[144:145], s[6:7], 0, v[136:137]
	s_add_i32 m0, s65, 0xe000
	s_nop 0
	global_load_lds_dwordx4 v[144:145], off
	s_waitcnt vmcnt(8)
	s_waitcnt lgkmcnt(0)
	s_barrier
	s_setprio 1
	s_waitcnt lgkmcnt(0)
	v_mfma_f32_16x16x32_bf16 v[126:129], v[140:143], v[176:179], v[126:129]
	v_mfma_f32_16x16x32_bf16 v[122:125], v[152:155], v[176:179], v[122:125]
	v_mfma_f32_16x16x32_bf16 v[110:113], v[140:143], v[188:191], v[110:113]
	v_mfma_f32_16x16x32_bf16 v[106:109], v[152:155], v[188:191], v[106:109]
	v_mfma_f32_16x16x32_bf16 v[94:97], v[140:143], v[196:199], v[94:97]
	v_mfma_f32_16x16x32_bf16 v[90:93], v[152:155], v[196:199], v[90:93]
	v_mfma_f32_16x16x32_bf16 v[76:79], v[140:143], v[204:207], v[76:79]
	v_mfma_f32_16x16x32_bf16 v[72:75], v[152:155], v[204:207], v[72:75]
	v_mfma_f32_16x16x32_bf16 v[126:129], v[148:151], v[180:183], v[126:129]
	v_mfma_f32_16x16x32_bf16 v[122:125], v[156:159], v[180:183], v[122:125]
	v_mfma_f32_16x16x32_bf16 v[110:113], v[148:151], v[192:195], v[110:113]
	v_mfma_f32_16x16x32_bf16 v[106:109], v[156:159], v[192:195], v[106:109]
	v_mfma_f32_16x16x32_bf16 v[94:97], v[148:151], v[200:203], v[94:97]
	v_mfma_f32_16x16x32_bf16 v[90:93], v[156:159], v[200:203], v[90:93]
	v_mfma_f32_16x16x32_bf16 v[76:79], v[148:151], v[208:211], v[76:79]
	v_mfma_f32_16x16x32_bf16 v[72:75], v[156:159], v[208:211], v[72:75]
	s_setprio 0
	s_setprio 1
	v_mfma_f32_16x16x32_bf16 v[118:121], v[160:163], v[176:179], v[118:121]
	v_mfma_f32_16x16x32_bf16 v[114:117], v[168:171], v[176:179], v[114:117]
	v_mfma_f32_16x16x32_bf16 v[102:105], v[160:163], v[188:191], v[102:105]
	v_mfma_f32_16x16x32_bf16 v[98:101], v[168:171], v[188:191], v[98:101]
	v_mfma_f32_16x16x32_bf16 v[86:89], v[160:163], v[196:199], v[86:89]
	v_mfma_f32_16x16x32_bf16 v[82:85], v[168:171], v[196:199], v[82:85]
	v_mfma_f32_16x16x32_bf16 v[68:71], v[160:163], v[204:207], v[68:71]
	v_mfma_f32_16x16x32_bf16 v[64:67], v[168:171], v[204:207], v[64:67]
	v_mfma_f32_16x16x32_bf16 v[118:121], v[164:167], v[180:183], v[118:121]
	v_mfma_f32_16x16x32_bf16 v[114:117], v[172:175], v[180:183], v[114:117]
	v_mfma_f32_16x16x32_bf16 v[102:105], v[164:167], v[192:195], v[102:105]
	v_mfma_f32_16x16x32_bf16 v[98:101], v[172:175], v[192:195], v[98:101]
	v_mfma_f32_16x16x32_bf16 v[86:89], v[164:167], v[200:203], v[86:89]
	v_mfma_f32_16x16x32_bf16 v[82:85], v[172:175], v[200:203], v[82:85]
	v_mfma_f32_16x16x32_bf16 v[68:71], v[164:167], v[208:211], v[68:71]
	v_mfma_f32_16x16x32_bf16 v[64:67], v[172:175], v[208:211], v[64:67]
	s_setprio 0
	s_barrier
	s_add_i32 s26, s90, s64
	v_lshl_add_u64 v[144:145], s[38:39], 0, v[80:81]
	s_mov_b32 m0, s26
	ds_read_b128 v[176:179], v147 offset:16384
	ds_read_b128 v[180:183], v147 offset:17408
	ds_read_b128 v[188:191], v147 offset:18432
	ds_read_b128 v[192:195], v147 offset:19456
	ds_read_b128 v[196:199], v147 offset:20480
	ds_read_b128 v[200:203], v147 offset:21504
	ds_read_b128 v[204:207], v147 offset:22528
	ds_read_b128 v[208:211], v147 offset:23552
	s_cmp_eq_u32 s100, 1
	s_cbranch_scc1 .Ln1_sp2
	global_load_lds_dwordx4 v[144:145], off
	s_add_i32 m0, s26, 0x2000
	s_add_u32 s26, s38, 0x40000
	v_lshl_add_u64 v[184:185], s[38:39], 0, v[130:131]
	s_addc_u32 s27, s39, 0
	s_add_i32 s90, s91, s64
	global_load_lds_dwordx4 v[184:185], off
	v_lshl_add_u64 v[186:187], s[26:27], 0, v[80:81]
	s_mov_b32 m0, s90
	v_lshl_add_u64 v[212:213], s[60:61], 0, v[132:133]
	global_load_lds_dwordx4 v[186:187], off
	v_lshl_add_u64 v[186:187], s[26:27], 0, v[130:131]
	s_add_i32 m0, s90, 0x2000
	s_nop 0
	global_load_lds_dwordx4 v[186:187], off
	v_lshl_add_u64 v[186:187], s[60:61], 0, v[134:135]
	s_mov_b32 m0, s65
	s_nop 0
	global_load_lds_dwordx4 v[186:187], off
	s_mov_b32 m0, s66
	s_nop 0
	global_load_lds_dwordx4 v[212:213], off
	s_waitcnt vmcnt(8)
	s_branch .Ln1_sp2_j
.Ln1_sp2:
	s_waitcnt vmcnt(2)
.Ln1_sp2_j:
	s_waitcnt lgkmcnt(0)
	s_barrier
	s_setprio 1
	s_waitcnt lgkmcnt(0)
	v_mfma_f32_16x16x32_bf16 v[60:63], v[140:143], v[176:179], v[60:63]
	v_mfma_f32_16x16x32_bf16 v[56:59], v[152:155], v[176:179], v[56:59]
	v_mfma_f32_16x16x32_bf16 v[44:47], v[140:143], v[188:191], v[44:47]
	v_mfma_f32_16x16x32_bf16 v[40:43], v[152:155], v[188:191], v[40:43]
	v_mfma_f32_16x16x32_bf16 v[28:31], v[140:143], v[196:199], v[28:31]
	v_mfma_f32_16x16x32_bf16 v[24:27], v[152:155], v[196:199], v[24:27]
	v_mfma_f32_16x16x32_bf16 v[12:15], v[140:143], v[204:207], v[12:15]
	v_mfma_f32_16x16x32_bf16 v[8:11], v[152:155], v[204:207], v[8:11]
	v_mfma_f32_16x16x32_bf16 v[60:63], v[148:151], v[180:183], v[60:63]
	v_mfma_f32_16x16x32_bf16 v[56:59], v[156:159], v[180:183], v[56:59]
	v_mfma_f32_16x16x32_bf16 v[44:47], v[148:151], v[192:195], v[44:47]
	v_mfma_f32_16x16x32_bf16 v[40:43], v[156:159], v[192:195], v[40:43]
	v_mfma_f32_16x16x32_bf16 v[28:31], v[148:151], v[200:203], v[28:31]
	v_mfma_f32_16x16x32_bf16 v[24:27], v[156:159], v[200:203], v[24:27]
	v_mfma_f32_16x16x32_bf16 v[12:15], v[148:151], v[208:211], v[12:15]
	v_mfma_f32_16x16x32_bf16 v[8:11], v[156:159], v[208:211], v[8:11]
	s_setprio 0
	s_setprio 1
	v_mfma_f32_16x16x32_bf16 v[52:55], v[160:163], v[176:179], v[52:55]
	v_mfma_f32_16x16x32_bf16 v[48:51], v[168:171], v[176:179], v[48:51]
	v_mfma_f32_16x16x32_bf16 v[36:39], v[160:163], v[188:191], v[36:39]
	v_mfma_f32_16x16x32_bf16 v[32:35], v[168:171], v[188:191], v[32:35]
	v_mfma_f32_16x16x32_bf16 v[20:23], v[160:163], v[196:199], v[20:23]
	v_mfma_f32_16x16x32_bf16 v[16:19], v[168:171], v[196:199], v[16:19]
	v_mfma_f32_16x16x32_bf16 v[4:7], v[160:163], v[204:207], v[4:7]
	v_mfma_f32_16x16x32_bf16 v[0:3], v[168:171], v[204:207], v[0:3]
	v_mfma_f32_16x16x32_bf16 v[52:55], v[164:167], v[180:183], v[52:55]
	v_mfma_f32_16x16x32_bf16 v[48:51], v[172:175], v[180:183], v[48:51]
	v_mfma_f32_16x16x32_bf16 v[36:39], v[164:167], v[192:195], v[36:39]
	v_mfma_f32_16x16x32_bf16 v[32:35], v[172:175], v[192:195], v[32:35]
	v_mfma_f32_16x16x32_bf16 v[20:23], v[164:167], v[200:203], v[20:23]
	v_mfma_f32_16x16x32_bf16 v[16:19], v[172:175], v[200:203], v[16:19]
	v_mfma_f32_16x16x32_bf16 v[4:7], v[164:167], v[208:211], v[4:7]
	v_mfma_f32_16x16x32_bf16 v[0:3], v[172:175], v[208:211], v[0:3]
	s_setprio 0
	s_barrier
	s_add_i32 s90, 0, 0x18000
	s_add_i32 s91, 0, 0x1c000
	v_add_u32_e32 v156, s90, v146
	v_add_u32_e32 v172, s91, v146
	ds_read_b128 v[140:143], v156
	ds_read_b128 v[148:151], v156 offset:1024
	ds_read_b128 v[152:155], v156 offset:2048
	ds_read_b128 v[156:159], v156 offset:3072
	ds_read_b128 v[160:163], v172
	ds_read_b128 v[164:167], v172 offset:1024
	ds_read_b128 v[168:171], v172 offset:2048
	ds_read_b128 v[172:175], v172 offset:3072
	s_add_u32 s26, s60, 0x40000
	s_addc_u32 s27, s61, 0
	s_mov_b32 m0, s67
	v_lshl_add_u64 v[214:215], s[26:27], 0, v[134:135]
	ds_read_b128 v[176:179], v147 offset:32768
	ds_read_b128 v[180:183], v147 offset:33792
	ds_read_b128 v[188:191], v147 offset:34816
	ds_read_b128 v[192:195], v147 offset:35840
	ds_read_b128 v[196:199], v147 offset:36864
	ds_read_b128 v[200:203], v147 offset:37888
	ds_read_b128 v[204:207], v147 offset:38912
	ds_read_b128 v[208:211], v147 offset:39936
	s_cmp_eq_u32 s100, 1
	s_cbranch_scc1 .Ln1_sp3
	global_load_lds_dwordx4 v[214:215], off
	v_lshl_add_u64 v[214:215], s[26:27], 0, v[132:133]
	s_mov_b32 m0, s70
	s_nop 0
	global_load_lds_dwordx4 v[214:215], off
	s_waitcnt vmcnt(8)
	s_branch .Ln1_sp3_j

.Ln1_sp3_j:
	s_waitcnt lgkmcnt(0)
	s_barrier
	s_setprio 1
	s_waitcnt lgkmcnt(0)
	v_mfma_f32_16x16x32_bf16 v[126:129], v[140:143], v[176:179], v[126:129]
	v_mfma_f32_16x16x32_bf16 v[122:125], v[152:155], v[176:179], v[122:125]
	v_mfma_f32_16x16x32_bf16 v[110:113], v[140:143], v[188:191], v[110:113]
	v_mfma_f32_16x16x32_bf16 v[106:109], v[152:155], v[188:191], v[106:109]
	v_mfma_f32_16x16x32_bf16 v[94:97], v[140:143], v[196:199], v[94:97]
	v_mfma_f32_16x16x32_bf16 v[90:93], v[152:155], v[196:199], v[90:93]
	v_mfma_f32_16x16x32_bf16 v[76:79], v[140:143], v[204:207], v[76:79]
	v_mfma_f32_16x16x32_bf16 v[72:75], v[152:155], v[204:207], v[72:75]
	v_mfma_f32_16x16x32_bf16 v[126:129], v[148:151], v[180:183], v[126:129]
	v_mfma_f32_16x16x32_bf16 v[122:125], v[156:159], v[180:183], v[122:125]
	v_mfma_f32_16x16x32_bf16 v[110:113], v[148:151], v[192:195], v[110:113]
	v_mfma_f32_16x16x32_bf16 v[106:109], v[156:159], v[192:195], v[106:109]
	v_mfma_f32_16x16x32_bf16 v[94:97], v[148:151], v[200:203], v[94:97]
	v_mfma_f32_16x16x32_bf16 v[90:93], v[156:159], v[200:203], v[90:93]
	v_mfma_f32_16x16x32_bf16 v[76:79], v[148:151], v[208:211], v[76:79]
	v_mfma_f32_16x16x32_bf16 v[72:75], v[156:159], v[208:211], v[72:75]
	s_setprio 0
	s_setprio 1
	v_mfma_f32_16x16x32_bf16 v[118:121], v[160:163], v[176:179], v[118:121]
	v_mfma_f32_16x16x32_bf16 v[114:117], v[168:171], v[176:179], v[114:117]
	v_mfma_f32_16x16x32_bf16 v[102:105], v[160:163], v[188:191], v[102:105]
	v_mfma_f32_16x16x32_bf16 v[98:101], v[168:171], v[188:191], v[98:101]
	v_mfma_f32_16x16x32_bf16 v[86:89], v[160:163], v[196:199], v[86:89]
	v_mfma_f32_16x16x32_bf16 v[82:85], v[168:171], v[196:199], v[82:85]
	v_mfma_f32_16x16x32_bf16 v[68:71], v[160:163], v[204:207], v[68:71]
	v_mfma_f32_16x16x32_bf16 v[64:67], v[168:171], v[204:207], v[64:67]
	v_mfma_f32_16x16x32_bf16 v[118:121], v[164:167], v[180:183], v[118:121]
	v_mfma_f32_16x16x32_bf16 v[114:117], v[172:175], v[180:183], v[114:117]
	v_mfma_f32_16x16x32_bf16 v[102:105], v[164:167], v[192:195], v[102:105]
	v_mfma_f32_16x16x32_bf16 v[98:101], v[172:175], v[192:195], v[98:101]
	v_mfma_f32_16x16x32_bf16 v[86:89], v[164:167], v[200:203], v[86:89]
	v_mfma_f32_16x16x32_bf16 v[82:85], v[172:175], v[200:203], v[82:85]
	v_mfma_f32_16x16x32_bf16 v[68:71], v[164:167], v[208:211], v[68:71]
	v_mfma_f32_16x16x32_bf16 v[64:67], v[172:175], v[208:211], v[64:67]
	s_setprio 0
	s_barrier
	s_add_i32 s26, s90, s64
	v_lshl_add_u64 v[144:145], v[144:145], 0, s[12:13]
	s_mov_b32 m0, s26
	ds_read_b128 v[176:179], v147 offset:49152
	ds_read_b128 v[180:183], v147 offset:50176
	ds_read_b128 v[188:191], v147 offset:51200
	ds_read_b128 v[192:195], v147 offset:52224
	ds_read_b128 v[196:199], v147 offset:53248
	ds_read_b128 v[200:203], v147 offset:54272
	ds_read_b128 v[204:207], v147 offset:55296
	ds_read_b128 v[208:211], v147 offset:56320
	s_cmp_eq_u32 s100, 1
	s_cbranch_scc1 .Ln1_sp4
	global_load_lds_dwordx4 v[144:145], off
	s_add_i32 m0, s26, 0x2000
	s_add_u32 s26, s38, 0x40080
	v_lshl_add_u64 v[144:145], v[184:185], 0, s[12:13]
	s_addc_u32 s27, s39, 0
	s_add_i32 s38, s91, s64
	global_load_lds_dwordx4 v[144:145], off
	v_lshl_add_u64 v[144:145], s[26:27], 0, v[80:81]
	s_mov_b32 m0, s38
	s_nop 0
	global_load_lds_dwordx4 v[144:145], off
	v_lshl_add_u64 v[144:145], s[26:27], 0, v[130:131]
	s_add_i32 m0, s38, 0x2000
	s_nop 0
	global_load_lds_dwordx4 v[144:145], off
	v_lshl_add_u64 v[144:145], v[186:187], 0, s[12:13]
	s_mov_b32 m0, s82
	s_nop 0
	global_load_lds_dwordx4 v[144:145], off
	v_lshl_add_u64 v[144:145], v[212:213], 0, s[12:13]
	s_mov_b32 m0, s83
	s_nop 0
	global_load_lds_dwordx4 v[144:145], off
	s_waitcnt vmcnt(8)
	s_branch .Ln1_sp4_j
.Ln1_sp4:
.Ln1_sp4_j:
	s_waitcnt lgkmcnt(0)
	s_barrier
	s_setprio 1
	s_waitcnt lgkmcnt(0)
	v_mfma_f32_16x16x32_bf16 v[60:63], v[140:143], v[176:179], v[60:63]
	v_mfma_f32_16x16x32_bf16 v[56:59], v[152:155], v[176:179], v[56:59]
	v_mfma_f32_16x16x32_bf16 v[44:47], v[140:143], v[188:191], v[44:47]
	v_mfma_f32_16x16x32_bf16 v[40:43], v[152:155], v[188:191], v[40:43]
	v_mfma_f32_16x16x32_bf16 v[28:31], v[140:143], v[196:199], v[28:31]
	v_mfma_f32_16x16x32_bf16 v[24:27], v[152:155], v[196:199], v[24:27]
	v_mfma_f32_16x16x32_bf16 v[12:15], v[140:143], v[204:207], v[12:15]
	v_mfma_f32_16x16x32_bf16 v[8:11], v[152:155], v[204:207], v[8:11]
	v_mfma_f32_16x16x32_bf16 v[60:63], v[148:151], v[180:183], v[60:63]
	v_mfma_f32_16x16x32_bf16 v[56:59], v[156:159], v[180:183], v[56:59]
	v_mfma_f32_16x16x32_bf16 v[44:47], v[148:151], v[192:195], v[44:47]
	v_mfma_f32_16x16x32_bf16 v[40:43], v[156:159], v[192:195], v[40:43]
	v_mfma_f32_16x16x32_bf16 v[28:31], v[148:151], v[200:203], v[28:31]
	v_mfma_f32_16x16x32_bf16 v[24:27], v[156:159], v[200:203], v[24:27]
	v_mfma_f32_16x16x32_bf16 v[12:15], v[148:151], v[208:211], v[12:15]
	v_mfma_f32_16x16x32_bf16 v[8:11], v[156:159], v[208:211], v[8:11]
	s_setprio 0
	s_setprio 1
	v_mfma_f32_16x16x32_bf16 v[52:55], v[160:163], v[176:179], v[52:55]
	v_mfma_f32_16x16x32_bf16 v[48:51], v[168:171], v[176:179], v[48:51]
	v_mfma_f32_16x16x32_bf16 v[36:39], v[160:163], v[188:191], v[36:39]
	v_mfma_f32_16x16x32_bf16 v[32:35], v[168:171], v[188:191], v[32:35]
	v_mfma_f32_16x16x32_bf16 v[20:23], v[160:163], v[196:199], v[20:23]
	v_mfma_f32_16x16x32_bf16 v[16:19], v[168:171], v[196:199], v[16:19]
	v_mfma_f32_16x16x32_bf16 v[4:7], v[160:163], v[204:207], v[4:7]
	v_mfma_f32_16x16x32_bf16 v[0:3], v[168:171], v[204:207], v[0:3]
	v_mfma_f32_16x16x32_bf16 v[52:55], v[164:167], v[180:183], v[52:55]
	v_mfma_f32_16x16x32_bf16 v[48:51], v[172:175], v[180:183], v[48:51]
	v_mfma_f32_16x16x32_bf16 v[36:39], v[164:167], v[192:195], v[36:39]
	v_mfma_f32_16x16x32_bf16 v[32:35], v[172:175], v[192:195], v[32:35]
	v_mfma_f32_16x16x32_bf16 v[20:23], v[164:167], v[200:203], v[20:23]
	v_mfma_f32_16x16x32_bf16 v[16:19], v[172:175], v[200:203], v[16:19]
	v_mfma_f32_16x16x32_bf16 v[4:7], v[164:167], v[208:211], v[4:7]
	v_mfma_f32_16x16x32_bf16 v[0:3], v[172:175], v[208:211], v[0:3]
	s_setprio 0
	s_barrier
	s_add_i32 s89, s89, 2
	s_add_u32 s87, s87, 0x100
	s_addc_u32 s88, s88, 0
	s_add_u32 s6, s6, 0x100
	s_addc_u32 s7, s7, 0
	s_cmp_gt_u32 s89, 13
	s_cbranch_scc0 .LBB0_234
	s_and_b64 vcc, exec, s[10:11]
	s_cbranch_vccz .LBB0_237
	s_barrier
